# attention: V fragment ds_reads for the first PV stage hoisted above the last softmax-pack VALU chunk
# baseline (speedup 1.0000x reference)
; #define SBAR() __builtin_amdgcn_sched_barrier(0)
; template <int I> __device__ __forceinline__ void fs_chunk(f32x16& p0, f32x16& p1, float alpha, float& l_reg, SMState& st, bf16x8& pa0, bf16x8& pa1, bf16x8& pa2, bf16x8& pa3) {
;     ...
;   if constexpr (I < 4) {
; #pragma unroll
;     for (int r = 4 * I; r < 4 * I + 4; ++r) p1[r] = __builtin_amdgcn_exp2f(p1[r]);
;     if constexpr (I == 0) st.ps = 0.f;
;   } else if constexpr (I < 8) { constexpr int j = 4 * (I - 4);
; #pragma unroll
;     for (int r = j; r < j + 4; ++r) st.ps += p0[r];
; #pragma unroll
;     for (int r = j; r < j + 4; ++r) st.ps += p1[r];
;   } else if constexpr (I == 8) {
;     const float ps_ = st.ps;
;     auto rr = __builtin_amdgcn_permlane32_swap(__float_as_uint(ps_), __float_as_uint(ps_), false, false);
;     l_reg = l_reg * alpha + (__uint_as_float(rr[0]) + __uint_as_float(rr[1]));
;     PK4(p0, 0, pa0);
;   } else if constexpr (I == 9) { PK4(p0, 8, pa1); }
;   else if constexpr (I == 10) { PK4(p1, 0, pa2); }
;   else { PK4(p1, 8, pa3); }
;     ...
; }
; template <int P> __device__ __forceinline__ void dma_piece(const DmaCtx& c) {
;   if constexpr (P < 3) __builtin_amdgcn_raw_ptr_buffer_load_lds(c.srd, (lds_u32_t*)(c.kd + (c.wid + 8 * P) * 1024), 16, c.koff[P], c.gk, 0, 0);
;   else __builtin_amdgcn_raw_ptr_buffer_load_lds(c.srd, (lds_u32_t*)(c.vd + (c.wid + 8 * (P - 3)) * 1024), 16, c.voff[P - 3], c.gv, 0, 0);
; }
; template <int D0> __device__ __forceinline__ void h1_stage(f32x16& pc0, f32x16& pc1, f32x16& pp0, f32x16& pp1, float alP, float& l_reg, SMState& st, bf16x8& pa0, bf16x8& pa1, bf16x8& pa2, bf16x8& pa3, ...
;   bf16x8 m0, m1, mq;
;   if constexpr (D0 < 10) kq_load<D0 + 2>(m0, m1, mq, Ks, qr, qlds, kb);
;   pc0 = __builtin_amdgcn_mfma_f32_32x32x16_bf16(b0, q, pc0, 0, 0, 0);
;   pc1 = __builtin_amdgcn_mfma_f32_32x32x16_bf16(b1, q, pc1, 0, 0, 0);
;   if constexpr (D0 >= 1 && D0 <= 5) dma_piece<D0 - 1>(dc);
;   SBAR(); fs_chunk<D0>(pp0, pp1, alP, l_reg, st, pa0, pa1, pa2, pa3); SBAR();
;   if constexpr (D0 < 11) h1_stage<D0 + 1>(pc0, pc1, pp0, pp1, alP, l_reg, st, pa0, pa1, pa2, pa3, n0, n1, nq, m0, m1, mq, Ks, qr, qlds, kb, dc);
; }
.Lattn_m2:
	v_xor_b32_e32 v112, 0x80000000, v191
	v_mov_b32_e32 v113, v112
	v_mov_b32_e32 v114, v112
	v_mov_b32_e32 v115, v112
	v_mov_b32_e32 v116, v112
	v_mov_b32_e32 v117, v112
	v_mov_b32_e32 v118, v112
	v_mov_b32_e32 v119, v112
	v_mov_b32_e32 v120, v112
	v_mov_b32_e32 v121, v112
	v_mov_b32_e32 v122, v112
	v_mov_b32_e32 v123, v112
	v_mov_b32_e32 v124, v112
	v_mov_b32_e32 v125, v112
	v_mov_b32_e32 v126, v112
	v_mov_b32_e32 v127, v112
	v_add_u32_e32 v224, s10, v199
	v_add_u32_e32 v225, s10, v200
	s_waitcnt lgkmcnt(1)
	v_mfma_f32_32x32x16_bf16 v[96:111], v[204:207], v[156:159], v[112:127]
	ds_read_b128 v[204:207], v224 offset:32768
	ds_read_b128 v[212:215], v224 offset:45056
	ds_read_b128 v[216:219], v225 offset:32768
	ds_read_b128 v[220:223], v225 offset:45056
	s_mul_i32 s11, s52, 0x6000
	s_add_i32 s53, s11, 0
	s_add_i32 s11, s51, 0xfffbe000
	s_waitcnt lgkmcnt(4)
	v_mfma_f32_32x32x16_bf16 v[112:127], v[208:211], v[156:159], v[112:127]
	v_exp_f32_e32 v226, v80
	v_exp_f32_e32 v227, v81
	v_exp_f32_e32 v228, v82
	v_exp_f32_e32 v229, v83
	v_add_u32_e32 v230, s10, v201
	s_add_i32 s10, s53, s69
	s_add_i32 m0, s10, 0x8000
	ds_read_b128 v[80:83], v230 offset:32768
	ds_read_b128 v[208:211], v230 offset:45056
	buffer_load_dwordx4 v194, s[28:31], s51 offen lds
	s_waitcnt lgkmcnt(5)
	v_mfma_f32_32x32x16_bf16 v[96:111], v[204:207], v[152:155], v[96:111]
	s_waitcnt lgkmcnt(4)
	v_mfma_f32_32x32x16_bf16 v[112:127], v[212:215], v[152:155], v[112:127]
	v_exp_f32_e32 v231, v84
	v_exp_f32_e32 v232, v85
	v_exp_f32_e32 v233, v86
	v_exp_f32_e32 v234, v87
	s_add_i32 m0, s10, 0xa000
	ds_read_b128 v[84:87], v203 offset:32896
	ds_read_b128 v[204:207], v203 offset:45184
	buffer_load_dwordx4 v195, s[28:31], s51 offen lds
	s_waitcnt lgkmcnt(5)
	v_mfma_f32_32x32x16_bf16 v[96:111], v[216:219], v[148:151], v[96:111]
	s_waitcnt lgkmcnt(4)
	v_mfma_f32_32x32x16_bf16 v[112:127], v[220:223], v[148:151], v[112:127]
	v_exp_f32_e32 v235, v88
	v_exp_f32_e32 v236, v89
	v_exp_f32_e32 v237, v90
	v_exp_f32_e32 v238, v91
	s_add_i32 m0, s10, 0xc000
	ds_read_b128 v[88:91], v224 offset:32896
	ds_read_b128 v[212:215], v224 offset:45184
	buffer_load_dwordx4 v196, s[28:31], s51 offen lds
	s_waitcnt lgkmcnt(5)
	v_mfma_f32_32x32x16_bf16 v[96:111], v[80:83], v[144:147], v[96:111]
	s_waitcnt lgkmcnt(4)
	v_mfma_f32_32x32x16_bf16 v[112:127], v[208:211], v[144:147], v[112:127]
	v_exp_f32_e32 v239, v92
	v_exp_f32_e32 v240, v93
	v_exp_f32_e32 v241, v94
	v_exp_f32_e32 v242, v95
	s_mov_b32 m0, s50
	ds_read_b128 v[80:83], v225 offset:32896
	ds_read_b128 v[92:95], v225 offset:45184
	buffer_load_dwordx4 v197, s[28:31], s11 offen lds
	s_waitcnt lgkmcnt(5)
	v_mfma_f32_32x32x16_bf16 v[96:111], v[84:87], v[140:143], v[96:111]
	s_waitcnt lgkmcnt(4)
	v_mfma_f32_32x32x16_bf16 v[112:127], v[204:207], v[140:143], v[112:127]
	v_add_f32_e32 v84, 0, v64
	v_add_f32_e32 v84, v65, v84
	v_add_f32_e32 v84, v66, v84
	v_add_f32_e32 v84, v67, v84
	v_add_f32_e32 v84, v226, v84
	v_add_f32_e32 v84, v227, v84
	v_add_f32_e32 v84, v228, v84
	v_add_f32_e32 v208, v229, v84
	s_mov_b32 m0, s49
	ds_read_b128 v[84:87], v230 offset:32896
	ds_read_b128 v[204:207], v230 offset:45184
	buffer_load_dwordx4 v198, s[28:31], s11 offen lds
	s_waitcnt lgkmcnt(5)
	v_mfma_f32_32x32x16_bf16 v[96:111], v[88:91], v[136:139], v[96:111]
	s_waitcnt lgkmcnt(4)
	v_mfma_f32_32x32x16_bf16 v[112:127], v[212:215], v[136:139], v[112:127]
	v_add_f32_e32 v88, v68, v208
	v_add_f32_e32 v88, v69, v88
	v_add_f32_e32 v88, v70, v88
	v_add_f32_e32 v88, v71, v88
	v_add_f32_e32 v88, v231, v88
	v_add_f32_e32 v88, v232, v88
	v_add_f32_e32 v88, v233, v88
	v_add_f32_e32 v212, v234, v88
	s_waitcnt lgkmcnt(3)
	v_mfma_f32_32x32x16_bf16 v[96:111], v[80:83], v[132:135], v[96:111]
	ds_read_b128 v[80:83], v203 offset:45312
	ds_read_b128 v[88:91], v203 offset:33024
	ds_read_b128 v[208:211], v192
	s_waitcnt lgkmcnt(5)
	v_mfma_f32_32x32x16_bf16 v[112:127], v[92:95], v[132:135], v[112:127]
	v_add_f32_e32 v92, v72, v212
	v_add_f32_e32 v92, v73, v92
	v_add_f32_e32 v92, v74, v92
	v_add_f32_e32 v92, v75, v92
	v_add_f32_e32 v92, v235, v92
	v_add_f32_e32 v92, v236, v92
	v_add_f32_e32 v92, v237, v92
	v_add_f32_e32 v203, v238, v92
	s_waitcnt lgkmcnt(4)
	v_mfma_f32_32x32x16_bf16 v[96:111], v[84:87], v[128:131], v[96:111]
	ds_read_b128 v[84:87], v224 offset:45312
	ds_read_b128 v[92:95], v224 offset:33024
	ds_read_b128 v[212:215], v192 offset:1024
	s_waitcnt lgkmcnt(6)
; #define SBAR() __builtin_amdgcn_sched_barrier(0)
; template <int I> __device__ __forceinline__ void fs_chunk(f32x16& p0, f32x16& p1, float alpha, float& l_reg, SMState& st, bf16x8& pa0, bf16x8& pa1, bf16x8& pa2, bf16x8& pa3) {
;     ...
;   if constexpr (I < 4) {
; #pragma unroll
;     for (int r = 4 * I; r < 4 * I + 4; ++r) p1[r] = __builtin_amdgcn_exp2f(p1[r]);
;     if constexpr (I == 0) st.ps = 0.f;
;   } else if constexpr (I < 8) { constexpr int j = 4 * (I - 4);
; #pragma unroll
;     for (int r = j; r < j + 4; ++r) st.ps += p0[r];
; #pragma unroll
;     for (int r = j; r < j + 4; ++r) st.ps += p1[r];
;   } else if constexpr (I == 8) {
;     const float ps_ = st.ps;
;     auto rr = __builtin_amdgcn_permlane32_swap(__float_as_uint(ps_), __float_as_uint(ps_), false, false);
;     l_reg = l_reg * alpha + (__uint_as_float(rr[0]) + __uint_as_float(rr[1]));
;     PK4(p0, 0, pa0);
;   } else if constexpr (I == 9) { PK4(p0, 8, pa1); }
;   else if constexpr (I == 10) { PK4(p1, 0, pa2); }
;   else { PK4(p1, 8, pa3); }
;     ...
; }
; template <int G> __device__ __forceinline__ void v_load(s16x4& la, s16x4& ha, s16x4& lb, s16x4& hb, const __attribute__((address_space(3))) char* vb) {
;   constexpr int ks = G >> 1, d0 = (G & 1) * 2;
;   la = __builtin_amdgcn_ds_read_tr16_b64_v4i16((lds_s16x4b*)(vb + v_rd_off(d0, ks, 0))); ha = __builtin_amdgcn_ds_read_tr16_b64_v4i16((lds_s16x4b*)(vb + v_rd_off(d0, ks, 1)));
;   lb = __builtin_amdgcn_ds_read_tr16_b64_v4i16((lds_s16x4b*)(vb + v_rd_off(d0 + 1, ks, 0))); hb = __builtin_amdgcn_ds_read_tr16_b64_v4i16((lds_s16x4b*)(vb + v_rd_off(d0 + 1, ks, 1)));
; }
; template <int G> __device__ __forceinline__ void h2_stage(f32x16* o, f32x16& pc0, f32x16& pc1, float& m_reg, float& alC, SMState& st, bf16x8 pa0, bf16x8 pa1, bf16x8 pa2, bf16x8 pa3, ...
;   constexpr int ks = G >> 1, d0 = (G & 1) * 2;
;   s16x4 nla, nha, nlb, nhb;
;   if constexpr (G < 7) v_load<G + 1>(nla, nha, nlb, nhb, vb);
;   const bf16x8 pa = ks == 0 ? pa0 : ks == 1 ? pa1 : ks == 2 ? pa2 : pa3;
;     ...
;   o[d0] = __builtin_amdgcn_mfma_f32_32x32x16_bf16(pa, PK(la, ha), o[d0], 0, 0, 0);
;   o[d0 + 1] = __builtin_amdgcn_mfma_f32_32x32x16_bf16(pa, PK(lb, hb), o[d0 + 1], 0, 0, 0);
;     ...
;   SBAR(); ps_chunk<G>(pc0, pc1, m_reg, alC, st); SBAR();
;   if constexpr (G < 7) h2_stage<G + 1>(o, pc0, pc1, m_reg, alC, st, pa0, pa1, pa2, pa3, nla, nha, nlb, nhb, vb);
; }
	v_mfma_f32_32x32x16_bf16 v[112:127], v[204:207], v[128:131], v[112:127]
	v_add_f32_e32 v203, v76, v203
	v_add_f32_e32 v203, v77, v203
	v_add_f32_e32 v203, v78, v203
	v_add_f32_e32 v203, v79, v203
	v_add_f32_e32 v203, v239, v203
	v_add_f32_e32 v203, v240, v203
	v_add_f32_e32 v203, v241, v203
	v_add_f32_e32 v203, v242, v203
	s_waitcnt lgkmcnt(3)
	v_mfma_f32_32x32x16_bf16 v[96:111], v[88:91], v[208:211], v[96:111]
	ds_read_b128 v[88:91], v225 offset:45312
	ds_read_b128 v[216:219], v225 offset:33024
	ds_read_b128 v[220:223], v192 offset:2048
	v_mfma_f32_32x32x16_bf16 v[112:127], v[80:83], v[208:211], v[112:127]
	v_mov_b32_e32 v204, v203
	v_cvt_pk_bf16_f32 v80, v64, v65
	v_cvt_pk_bf16_f32 v81, v66, v67
	v_cvt_pk_bf16_f32 v82, v68, v69
	v_cvt_pk_bf16_f32 v83, v70, v71
	v_permlane32_swap_b32_e32 v203, v204
	v_permlane32_swap_b32_e32 v80, v82
	v_permlane32_swap_b32_e32 v81, v83
	s_waitcnt lgkmcnt(3)
	v_mfma_f32_32x32x16_bf16 v[96:111], v[92:95], v[212:215], v[96:111]
	ds_read_b128 v[64:67], v192 offset:3072
	ds_read_b128 v[92:95], v230 offset:33024
	ds_read_b128 v[206:209], v230 offset:45312
	v_mfma_f32_32x32x16_bf16 v[112:127], v[84:87], v[212:215], v[112:127]
	v_cvt_pk_bf16_f32 v72, v72, v73
	v_cvt_pk_bf16_f32 v73, v74, v75
	v_cvt_pk_bf16_f32 v74, v76, v77
	v_cvt_pk_bf16_f32 v75, v78, v79
	s_nop 0
	v_permlane32_swap_b32_e32 v72, v74
	v_permlane32_swap_b32_e32 v73, v75
	s_waitcnt lgkmcnt(3)
	v_mfma_f32_32x32x16_bf16 v[96:111], v[216:219], v[220:223], v[96:111]
	v_mfma_f32_32x32x16_bf16 v[112:127], v[88:91], v[220:223], v[112:127]
	v_cvt_pk_bf16_f32 v68, v226, v227
	v_cvt_pk_bf16_f32 v69, v228, v229
	v_cvt_pk_bf16_f32 v70, v231, v232
	v_cvt_pk_bf16_f32 v71, v233, v234
	s_nop 0
	v_permlane32_swap_b32_e32 v68, v70
	v_permlane32_swap_b32_e32 v69, v71
	s_waitcnt lgkmcnt(1)
	v_mfma_f32_32x32x16_bf16 v[96:111], v[92:95], v[64:67], v[96:111]
	s_waitcnt lgkmcnt(0)
	v_mfma_f32_32x32x16_bf16 v[112:127], v[206:209], v[64:67], v[112:127]
	ds_read_b64_tr_b16 v[78:79], v188 offset:2048
	ds_read_b64_tr_b16 v[76:77], v188
	ds_read_b64_tr_b16 v[84:85], v188 offset:512
	ds_read_b64_tr_b16 v[88:89], v188 offset:1024
	ds_read_b64_tr_b16 v[92:93], v188 offset:1536
	ds_read_b64_tr_b16 v[86:87], v188 offset:2560
	ds_read_b64_tr_b16 v[90:91], v188 offset:3072
	ds_read_b64_tr_b16 v[94:95], v188 offset:3584
	v_cvt_pk_bf16_f32 v64, v235, v236
	v_cvt_pk_bf16_f32 v65, v237, v238
	v_cvt_pk_bf16_f32 v66, v239, v240
	v_cvt_pk_bf16_f32 v67, v241, v242
	s_nop 0
	v_permlane32_swap_b32_e32 v64, v66
	v_permlane32_swap_b32_e32 v65, v67
	s_waitcnt lgkmcnt(6)
	v_mfma_f32_32x32x16_bf16 v[0:15], v[80:83], v[76:79], v[0:15]
	s_waitcnt lgkmcnt(2)
	v_mfma_f32_32x32x16_bf16 v[48:63], v[80:83], v[84:87], v[48:63]
	v_max_f32_e32 v76, v97, v97
	v_max_f32_e32 v77, v96, v96
	v_max_f32_e32 v76, v77, v76
	v_max3_f32 v76, v76, v98, v99
	v_max3_f32 v76, v76, v100, v101
	v_max3_f32 v76, v76, v102, v103
	v_max3_f32 v76, v76, v104, v105
	v_max3_f32 v76, v76, v106, v107
	v_max3_f32 v76, v76, v108, v109
	v_max3_f32 v84, v76, v110, v111
	s_waitcnt lgkmcnt(1)
	v_mfma_f32_32x32x16_bf16 v[32:47], v[80:83], v[88:91], v[32:47]
	ds_read_b64_tr_b16 v[76:77], v188 offset:4096
	ds_read_b64_tr_b16 v[78:79], v188 offset:6144
	ds_read_b64_tr_b16 v[88:89], v188 offset:6656
	ds_read_b64_tr_b16 v[86:87], v188 offset:4608
	s_waitcnt lgkmcnt(4)
	v_mfma_f32_32x32x16_bf16 v[16:31], v[80:83], v[92:95], v[16:31]
	v_max3_f32 v80, v84, v112, v113
	v_max3_f32 v80, v80, v114, v115
	v_max3_f32 v80, v80, v116, v117
	v_max3_f32 v80, v80, v118, v119
	v_max3_f32 v80, v80, v120, v121
	v_max3_f32 v80, v80, v122, v123
	v_max3_f32 v80, v80, v124, v125
	v_max3_f32 v80, v80, v126, v127
	v_mov_b32_e32 v81, v80
	s_nop 1
	v_permlane32_swap_b32_e32 v80, v81
	v_max_f32_e32 v81, v81, v81
	v_max_f32_e32 v80, v80, v80
	v_max_f32_e32 v84, v80, v81
	s_waitcnt lgkmcnt(2)
	v_mfma_f32_32x32x16_bf16 v[0:15], v[72:75], v[76:79], v[0:15]
	ds_read_b64_tr_b16 v[80:81], v188 offset:5120
	ds_read_b64_tr_b16 v[82:83], v188 offset:7168
	ds_read_b64_tr_b16 v[78:79], v188 offset:7680
	ds_read_b64_tr_b16 v[76:77], v188 offset:5632
	s_waitcnt lgkmcnt(4)
	v_mfma_f32_32x32x16_bf16 v[48:63], v[72:75], v[86:89], v[48:63]
	v_cmp_ge_f32_e32 vcc, s67, v84
	s_cmp_eq_u64 vcc, exec
	s_cbranch_scc0 .LBB0_668
	v_mov_b32_e32 v206, 1.0

; #define SBAR() __builtin_amdgcn_sched_barrier(0)
; template <int I> __device__ __forceinline__ void fs_chunk(f32x16& p0, f32x16& p1, float alpha, float& l_reg, SMState& st, bf16x8& pa0, bf16x8& pa1, bf16x8& pa2, bf16x8& pa3) {
;     ...
;   if constexpr (I < 4) {
; #pragma unroll
;     for (int r = 4 * I; r < 4 * I + 4; ++r) p1[r] = __builtin_amdgcn_exp2f(p1[r]);
;     if constexpr (I == 0) st.ps = 0.f;
;   } else if constexpr (I < 8) { constexpr int j = 4 * (I - 4);
; #pragma unroll
;     for (int r = j; r < j + 4; ++r) st.ps += p0[r];
; #pragma unroll
;     for (int r = j; r < j + 4; ++r) st.ps += p1[r];
;   } else if constexpr (I == 8) {
;     const float ps_ = st.ps;
;     auto rr = __builtin_amdgcn_permlane32_swap(__float_as_uint(ps_), __float_as_uint(ps_), false, false);
;     l_reg = l_reg * alpha + (__uint_as_float(rr[0]) + __uint_as_float(rr[1]));
;     PK4(p0, 0, pa0);
;   } else if constexpr (I == 9) { PK4(p0, 8, pa1); }
;   else if constexpr (I == 10) { PK4(p1, 0, pa2); }
;   else { PK4(p1, 8, pa3); }
;     ...
; }
; template <int P> __device__ __forceinline__ void dma_piece(const DmaCtx& c) {
;   if constexpr (P < 3) __builtin_amdgcn_raw_ptr_buffer_load_lds(c.srd, (lds_u32_t*)(c.kd + (c.wid + 8 * P) * 1024), 16, c.koff[P], c.gk, 0, 0);
;   else __builtin_amdgcn_raw_ptr_buffer_load_lds(c.srd, (lds_u32_t*)(c.vd + (c.wid + 8 * (P - 3)) * 1024), 16, c.voff[P - 3], c.gv, 0, 0);
; }
; template <int D0> __device__ __forceinline__ void h1_stage(f32x16& pc0, f32x16& pc1, f32x16& pp0, f32x16& pp1, float alP, float& l_reg, SMState& st, bf16x8& pa0, bf16x8& pa1, bf16x8& pa2, bf16x8& pa3, ...
;   bf16x8 m0, m1, mq;
;   if constexpr (D0 < 10) kq_load<D0 + 2>(m0, m1, mq, Ks, qr, qlds, kb);
;   pc0 = __builtin_amdgcn_mfma_f32_32x32x16_bf16(b0, q, pc0, 0, 0, 0);
;   pc1 = __builtin_amdgcn_mfma_f32_32x32x16_bf16(b1, q, pc1, 0, 0, 0);
;   if constexpr (D0 >= 1 && D0 <= 5) dma_piece<D0 - 1>(dc);
;   SBAR(); fs_chunk<D0>(pp0, pp1, alP, l_reg, st, pa0, pa1, pa2, pa3); SBAR();
;   if constexpr (D0 < 11) h1_stage<D0 + 1>(pc0, pc1, pp0, pp1, alP, l_reg, st, pa0, pa1, pa2, pa3, n0, n1, nq, m0, m1, mq, Ks, qr, qlds, kb, dc);
; }
.Lattn_m1:
	v_xor_b32_e32 v80, 0x80000000, v191
	v_mov_b32_e32 v81, v80
	v_mov_b32_e32 v82, v80
	v_mov_b32_e32 v83, v80
	v_mov_b32_e32 v84, v80
	v_mov_b32_e32 v85, v80
	v_mov_b32_e32 v86, v80
	v_mov_b32_e32 v87, v80
	v_mov_b32_e32 v88, v80
	v_mov_b32_e32 v89, v80
	v_mov_b32_e32 v90, v80
	v_mov_b32_e32 v91, v80
	v_mov_b32_e32 v92, v80
	v_mov_b32_e32 v93, v80
	v_mov_b32_e32 v94, v80
	v_mov_b32_e32 v95, v80
	v_add_u32_e32 v207, s53, v199
	v_add_u32_e32 v228, s53, v200
	s_waitcnt lgkmcnt(1)
	v_mfma_f32_32x32x16_bf16 v[64:79], v[208:211], v[156:159], v[80:95]
	s_add_i32 s10, s51, 0x42000
	s_add_i32 s11, s52, 1
	ds_read_b128 v[208:211], v207 offset:32768
	ds_read_b128 v[216:219], v207 offset:45056
	ds_read_b128 v[220:223], v228 offset:32768
	ds_read_b128 v[224:227], v228 offset:45056
	s_cmp_lg_u32 s52, 2
	s_cselect_b32 s73, s11, 0
	s_mul_i32 s11, s73, 0x6000
	s_waitcnt lgkmcnt(4)
	v_mfma_f32_32x32x16_bf16 v[80:95], v[212:215], v[156:159], v[80:95]
	s_add_i32 s52, s11, 0
	v_exp_f32_e32 v229, v112
	v_exp_f32_e32 v230, v113
	v_exp_f32_e32 v231, v114
	v_exp_f32_e32 v232, v115
	s_add_i32 s11, s52, s69
	v_add_u32_e32 v233, s53, v201
	s_add_i32 m0, s11, 0x8000
	ds_read_b128 v[112:115], v233 offset:32768
	ds_read_b128 v[212:215], v233 offset:45056
	buffer_load_dwordx4 v194, s[28:31], s10 offen lds
	s_waitcnt lgkmcnt(5)
	v_mfma_f32_32x32x16_bf16 v[64:79], v[208:211], v[152:155], v[64:79]
	s_waitcnt lgkmcnt(4)
	v_mfma_f32_32x32x16_bf16 v[80:95], v[216:219], v[152:155], v[80:95]
	v_exp_f32_e32 v234, v116
	v_exp_f32_e32 v235, v117
	v_exp_f32_e32 v236, v118
	v_exp_f32_e32 v237, v119
	s_add_i32 m0, s11, 0xa000
	ds_read_b128 v[116:119], v205 offset:32896
	ds_read_b128 v[208:211], v205 offset:45184
	buffer_load_dwordx4 v195, s[28:31], s10 offen lds
	s_waitcnt lgkmcnt(5)
	v_mfma_f32_32x32x16_bf16 v[64:79], v[220:223], v[148:151], v[64:79]
	s_waitcnt lgkmcnt(4)
	v_mfma_f32_32x32x16_bf16 v[80:95], v[224:227], v[148:151], v[80:95]
	v_exp_f32_e32 v238, v120
	v_exp_f32_e32 v239, v121
	v_exp_f32_e32 v240, v122
	v_exp_f32_e32 v241, v123
	s_add_i32 m0, s11, 0xc000
	ds_read_b128 v[120:123], v207 offset:32896
	ds_read_b128 v[216:219], v207 offset:45184
	buffer_load_dwordx4 v196, s[28:31], s10 offen lds
	s_waitcnt lgkmcnt(5)
	v_mfma_f32_32x32x16_bf16 v[64:79], v[112:115], v[144:147], v[64:79]
	s_waitcnt lgkmcnt(4)
	v_mfma_f32_32x32x16_bf16 v[80:95], v[212:215], v[144:147], v[80:95]
	v_exp_f32_e32 v242, v124
	v_exp_f32_e32 v243, v125
	v_exp_f32_e32 v244, v126
	v_exp_f32_e32 v245, v127
	s_mov_b32 m0, s70
	ds_read_b128 v[112:115], v228 offset:32896
	ds_read_b128 v[124:127], v228 offset:45184
	buffer_load_dwordx4 v197, s[28:31], s51 offen lds
	s_waitcnt lgkmcnt(5)
	v_mfma_f32_32x32x16_bf16 v[64:79], v[116:119], v[140:143], v[64:79]
	s_waitcnt lgkmcnt(4)
	v_mfma_f32_32x32x16_bf16 v[80:95], v[208:211], v[140:143], v[80:95]
	v_add_f32_e32 v116, 0, v96
	v_add_f32_e32 v116, v97, v116
	v_add_f32_e32 v116, v98, v116
	v_add_f32_e32 v116, v99, v116
	v_add_f32_e32 v116, v229, v116
	v_add_f32_e32 v116, v230, v116
	v_add_f32_e32 v116, v231, v116
	v_add_f32_e32 v212, v232, v116
	s_mov_b32 m0, s71
	ds_read_b128 v[116:119], v233 offset:32896
	ds_read_b128 v[208:211], v233 offset:45184
	buffer_load_dwordx4 v198, s[28:31], s51 offen lds
	s_waitcnt lgkmcnt(5)
	v_mfma_f32_32x32x16_bf16 v[64:79], v[120:123], v[136:139], v[64:79]
	s_waitcnt lgkmcnt(4)
	v_mfma_f32_32x32x16_bf16 v[80:95], v[216:219], v[136:139], v[80:95]
	v_add_f32_e32 v120, v100, v212
	v_add_f32_e32 v120, v101, v120
	v_add_f32_e32 v120, v102, v120
	v_add_f32_e32 v120, v103, v120
	v_add_f32_e32 v120, v234, v120
	v_add_f32_e32 v120, v235, v120
	v_add_f32_e32 v120, v236, v120
	v_add_f32_e32 v216, v237, v120
	s_waitcnt lgkmcnt(3)
	v_mfma_f32_32x32x16_bf16 v[64:79], v[112:115], v[132:135], v[64:79]
	ds_read_b128 v[112:115], v205 offset:45312
	ds_read_b128 v[120:123], v205 offset:33024
	ds_read_b128 v[212:215], v192
	s_waitcnt lgkmcnt(5)
	v_mfma_f32_32x32x16_bf16 v[80:95], v[124:127], v[132:135], v[80:95]
	v_add_f32_e32 v124, v104, v216
	v_add_f32_e32 v124, v105, v124
	v_add_f32_e32 v124, v106, v124
	v_add_f32_e32 v124, v107, v124
	v_add_f32_e32 v124, v238, v124
	v_add_f32_e32 v124, v239, v124
	v_add_f32_e32 v124, v240, v124
	v_add_f32_e32 v205, v241, v124
	s_waitcnt lgkmcnt(4)
	v_mfma_f32_32x32x16_bf16 v[64:79], v[116:119], v[128:131], v[64:79]
	ds_read_b128 v[124:127], v207 offset:45312
	ds_read_b128 v[216:219], v207 offset:33024
	ds_read_b128 v[220:223], v192 offset:1024
	s_waitcnt lgkmcnt(6)
; #define SBAR() __builtin_amdgcn_sched_barrier(0)
; template <int I> __device__ __forceinline__ void fs_chunk(f32x16& p0, f32x16& p1, float alpha, float& l_reg, SMState& st, bf16x8& pa0, bf16x8& pa1, bf16x8& pa2, bf16x8& pa3) {
;     ...
;   if constexpr (I < 4) {
; #pragma unroll
;     for (int r = 4 * I; r < 4 * I + 4; ++r) p1[r] = __builtin_amdgcn_exp2f(p1[r]);
;     if constexpr (I == 0) st.ps = 0.f;
;   } else if constexpr (I < 8) { constexpr int j = 4 * (I - 4);
; #pragma unroll
;     for (int r = j; r < j + 4; ++r) st.ps += p0[r];
; #pragma unroll
;     for (int r = j; r < j + 4; ++r) st.ps += p1[r];
;   } else if constexpr (I == 8) {
;     const float ps_ = st.ps;
;     auto rr = __builtin_amdgcn_permlane32_swap(__float_as_uint(ps_), __float_as_uint(ps_), false, false);
;     l_reg = l_reg * alpha + (__uint_as_float(rr[0]) + __uint_as_float(rr[1]));
;     PK4(p0, 0, pa0);
;   } else if constexpr (I == 9) { PK4(p0, 8, pa1); }
;   else if constexpr (I == 10) { PK4(p1, 0, pa2); }
;   else { PK4(p1, 8, pa3); }
;     ...
; }
; template <int G> __device__ __forceinline__ void v_load(s16x4& la, s16x4& ha, s16x4& lb, s16x4& hb, const __attribute__((address_space(3))) char* vb) {
;   constexpr int ks = G >> 1, d0 = (G & 1) * 2;
;   la = __builtin_amdgcn_ds_read_tr16_b64_v4i16((lds_s16x4b*)(vb + v_rd_off(d0, ks, 0))); ha = __builtin_amdgcn_ds_read_tr16_b64_v4i16((lds_s16x4b*)(vb + v_rd_off(d0, ks, 1)));
;   lb = __builtin_amdgcn_ds_read_tr16_b64_v4i16((lds_s16x4b*)(vb + v_rd_off(d0 + 1, ks, 0))); hb = __builtin_amdgcn_ds_read_tr16_b64_v4i16((lds_s16x4b*)(vb + v_rd_off(d0 + 1, ks, 1)));
; }
; template <int G> __device__ __forceinline__ void h2_stage(f32x16* o, f32x16& pc0, f32x16& pc1, float& m_reg, float& alC, SMState& st, bf16x8 pa0, bf16x8 pa1, bf16x8 pa2, bf16x8 pa3, ...
;   constexpr int ks = G >> 1, d0 = (G & 1) * 2;
;   s16x4 nla, nha, nlb, nhb;
;   if constexpr (G < 7) v_load<G + 1>(nla, nha, nlb, nhb, vb);
;   const bf16x8 pa = ks == 0 ? pa0 : ks == 1 ? pa1 : ks == 2 ? pa2 : pa3;
;     ...
;   o[d0] = __builtin_amdgcn_mfma_f32_32x32x16_bf16(pa, PK(la, ha), o[d0], 0, 0, 0);
;   o[d0 + 1] = __builtin_amdgcn_mfma_f32_32x32x16_bf16(pa, PK(lb, hb), o[d0 + 1], 0, 0, 0);
;     ...
;   SBAR(); ps_chunk<G>(pc0, pc1, m_reg, alC, st); SBAR();
;   if constexpr (G < 7) h2_stage<G + 1>(o, pc0, pc1, m_reg, alC, st, pa0, pa1, pa2, pa3, nla, nha, nlb, nhb, vb);
; }
	v_mfma_f32_32x32x16_bf16 v[80:95], v[208:211], v[128:131], v[80:95]
	v_add_f32_e32 v116, v108, v205
	v_add_f32_e32 v116, v109, v116
	v_add_f32_e32 v116, v110, v116
	v_add_f32_e32 v116, v111, v116
	v_add_f32_e32 v116, v242, v116
	v_add_f32_e32 v116, v243, v116
	v_add_f32_e32 v116, v244, v116
	v_add_f32_e32 v116, v245, v116
	s_waitcnt lgkmcnt(3)
	v_mfma_f32_32x32x16_bf16 v[64:79], v[120:123], v[212:215], v[64:79]
	ds_read_b128 v[118:121], v228 offset:45312
	ds_read_b128 v[208:211], v228 offset:33024
	ds_read_b128 v[224:227], v192 offset:2048
	v_mfma_f32_32x32x16_bf16 v[80:95], v[112:115], v[212:215], v[80:95]
	v_mov_b32_e32 v117, v116
	v_cvt_pk_bf16_f32 v112, v96, v97
	v_cvt_pk_bf16_f32 v113, v98, v99
	v_cvt_pk_bf16_f32 v114, v100, v101
	v_cvt_pk_bf16_f32 v115, v102, v103
	v_permlane32_swap_b32_e32 v116, v117
	v_permlane32_swap_b32_e32 v112, v114
	v_permlane32_swap_b32_e32 v113, v115
	s_waitcnt lgkmcnt(3)
	v_mfma_f32_32x32x16_bf16 v[64:79], v[216:219], v[220:223], v[64:79]
	ds_read_b128 v[96:99], v192 offset:3072
	ds_read_b128 v[212:215], v233 offset:33024
	ds_read_b128 v[216:219], v233 offset:45312
	v_mfma_f32_32x32x16_bf16 v[80:95], v[124:127], v[220:223], v[80:95]
	v_cvt_pk_bf16_f32 v104, v104, v105
	v_cvt_pk_bf16_f32 v105, v106, v107
	v_cvt_pk_bf16_f32 v106, v108, v109
	v_cvt_pk_bf16_f32 v107, v110, v111
	s_nop 0
	v_permlane32_swap_b32_e32 v104, v106
	v_permlane32_swap_b32_e32 v105, v107
	s_waitcnt lgkmcnt(3)
	v_mfma_f32_32x32x16_bf16 v[64:79], v[208:211], v[224:227], v[64:79]
	v_mfma_f32_32x32x16_bf16 v[80:95], v[118:121], v[224:227], v[80:95]
	v_cvt_pk_bf16_f32 v100, v229, v230
	v_cvt_pk_bf16_f32 v101, v231, v232
	v_cvt_pk_bf16_f32 v102, v234, v235
	v_cvt_pk_bf16_f32 v103, v236, v237
	s_nop 0
	v_permlane32_swap_b32_e32 v100, v102
	v_permlane32_swap_b32_e32 v101, v103
	s_waitcnt lgkmcnt(1)
	v_mfma_f32_32x32x16_bf16 v[64:79], v[212:215], v[96:99], v[64:79]
	s_waitcnt lgkmcnt(0)
	v_mfma_f32_32x32x16_bf16 v[80:95], v[216:219], v[96:99], v[80:95]
	ds_read_b64_tr_b16 v[110:111], v188 offset:18432
	ds_read_b64_tr_b16 v[108:109], v188 offset:16384
	ds_read_b64_tr_b16 v[118:119], v188 offset:16896
	ds_read_b64_tr_b16 v[122:123], v188 offset:17408
	ds_read_b64_tr_b16 v[208:209], v188 offset:17920
	ds_read_b64_tr_b16 v[120:121], v188 offset:18944
	ds_read_b64_tr_b16 v[124:125], v188 offset:19456
	ds_read_b64_tr_b16 v[210:211], v188 offset:19968
	v_cvt_pk_bf16_f32 v96, v238, v239
	v_cvt_pk_bf16_f32 v97, v240, v241
	v_cvt_pk_bf16_f32 v98, v242, v243
	v_cvt_pk_bf16_f32 v99, v244, v245
	s_nop 0
	v_permlane32_swap_b32_e32 v96, v98
	v_permlane32_swap_b32_e32 v97, v99
	s_waitcnt lgkmcnt(6)
	v_mfma_f32_32x32x16_bf16 v[0:15], v[112:115], v[108:111], v[0:15]
	s_waitcnt lgkmcnt(2)
	v_mfma_f32_32x32x16_bf16 v[48:63], v[112:115], v[118:121], v[48:63]
	v_max_f32_e32 v108, v65, v65
	v_max_f32_e32 v109, v64, v64
	v_max_f32_e32 v108, v109, v108
	v_max3_f32 v108, v108, v66, v67
	v_max3_f32 v108, v108, v68, v69
	v_max3_f32 v108, v108, v70, v71
	v_max3_f32 v108, v108, v72, v73
	v_max3_f32 v108, v108, v74, v75
	v_max3_f32 v108, v108, v76, v77
	v_max3_f32 v118, v108, v78, v79
	s_waitcnt lgkmcnt(1)
	v_mfma_f32_32x32x16_bf16 v[32:47], v[112:115], v[122:125], v[32:47]
	ds_read_b64_tr_b16 v[108:109], v188 offset:20480
	ds_read_b64_tr_b16 v[110:111], v188 offset:22528
	ds_read_b64_tr_b16 v[122:123], v188 offset:23040
	ds_read_b64_tr_b16 v[120:121], v188 offset:20992
	s_waitcnt lgkmcnt(4)
	v_mfma_f32_32x32x16_bf16 v[16:31], v[112:115], v[208:211], v[16:31]
	v_max3_f32 v112, v118, v80, v81
	v_max3_f32 v112, v112, v82, v83
	v_max3_f32 v112, v112, v84, v85
	v_max3_f32 v112, v112, v86, v87
	v_max3_f32 v112, v112, v88, v89
	v_max3_f32 v112, v112, v90, v91
	v_max3_f32 v112, v112, v92, v93
	v_max3_f32 v112, v112, v94, v95
	v_mov_b32_e32 v113, v112
	s_nop 1
	v_permlane32_swap_b32_e32 v112, v113
	v_max_f32_e32 v113, v113, v113
	v_max_f32_e32 v112, v112, v112
	v_max_f32_e32 v118, v112, v113
	s_waitcnt lgkmcnt(2)
	v_mfma_f32_32x32x16_bf16 v[0:15], v[104:107], v[108:111], v[0:15]
	ds_read_b64_tr_b16 v[112:113], v188 offset:21504
	ds_read_b64_tr_b16 v[114:115], v188 offset:23552
	ds_read_b64_tr_b16 v[110:111], v188 offset:24064
	ds_read_b64_tr_b16 v[108:109], v188 offset:22016
	s_waitcnt lgkmcnt(4)
	v_mfma_f32_32x32x16_bf16 v[48:63], v[104:107], v[120:123], v[48:63]
	v_cmp_ge_f32_e32 vcc, s67, v118
	s_cmp_eq_u64 vcc, exec
	v_mov_b32_e32 v205, 1.0
	s_cbranch_scc0 .LBB0_669
